# attention: loop control and next-tile V base folded into the last PV gaps; exit test before the barrier
# speedup vs baseline: 1.0610x; 1.0003x over previous
; #define SBAR() __builtin_amdgcn_sched_barrier(0)
; __device__ __forceinline__ s16x4 vtr(lds_cptr p){ return __builtin_bit_cast(s16x4,__builtin_amdgcn_ds_read_tr16_b64_v4i16((__attribute__((address_space(3))) v4i16_t*)p)); }
; template<int THRL> __device__ __forceinline__ void attn_unit(int qb,const bf16*Q,const bf16*__restrict__ K,const bf16*__restrict__ V,bf16*O,char*shm){
;     ...
;     bf16x8 kf[8]; kload8(kf,kp0+c0*SLOTB);
;     SBAR();
;     f32x16 C0,C1;
;     {
;       C0=__builtin_amdgcn_mfma_f32_32x32x16_bf16(kf[0],qr[0],negm,0,0,0); C1=__builtin_amdgcn_mfma_f32_32x32x16_bf16(kf[1],qr[0],negm,0,0,0);
;       C0=__builtin_amdgcn_mfma_f32_32x32x16_bf16(kf[2],qr[1],C0,0,0,0);   C1=__builtin_amdgcn_mfma_f32_32x32x16_bf16(kf[3],qr[1],C1,0,0,0);
;       C0=__builtin_amdgcn_mfma_f32_32x32x16_bf16(kf[4],qr[2],C0,0,0,0);   C1=__builtin_amdgcn_mfma_f32_32x32x16_bf16(kf[5],qr[2],C1,0,0,0);
;       C0=__builtin_amdgcn_mfma_f32_32x32x16_bf16(kf[6],qr[3],C0,0,0,0);   C1=__builtin_amdgcn_mfma_f32_32x32x16_bf16(kf[7],qr[3],C1,0,0,0); }
;     SBAR();
;     const lds_cptr vp_=vp0+c0*VSLOTB; s16x4 vl_[8],vh_[8];
;     #pragma unroll
;     for(int k2=0;k2<2;++k2)
;       #pragma unroll
;       for(int d_=0;d_<4;++d_){ vl_[d_*2+k2]=vtr(vp_+(d_*4096+k2*1024)); vh_[d_*2+k2]=vtr(vp_+(d_*4096+k2*1024+512)); }
;     SBAR();
;     { const int jb_=t-(NT-4); if(jb_>=0)cmask(C0,C1,jb_,qrel,hi); }
.LBB0_364:
	s_add_i32 s12, s31, 3
	s_cmp_ge_i32 s12, s26
	s_cselect_b64 s[12:13], -1, 0
	s_mov_b32 s34, s35
	s_and_b64 vcc, exec, s[12:13]
.LBB0_366:
	s_lshl_b32 s14, s34, 14
	v_add_u32_e32 v193, s14, v190
.Lattn_top:
	v_mfma_f32_32x32x16_bf16 v[80:95], v[236:239], v[112:115], v[64:79]
	ds_read_b64_tr_b16 v[156:157], v193 offset:24576
	ds_read_b64_tr_b16 v[158:159], v193 offset:25088
	v_mfma_f32_32x32x16_bf16 v[80:95], v[240:243], v[116:119], v[80:95]
	ds_read_b64_tr_b16 v[140:141], v193 offset:25600
	ds_read_b64_tr_b16 v[142:143], v193 offset:26112
	v_mfma_f32_32x32x16_bf16 v[80:95], v[244:247], v[120:123], v[80:95]
	ds_read_b64_tr_b16 v[152:153], v193 offset:28672
	ds_read_b64_tr_b16 v[154:155], v193 offset:29184
	v_mfma_f32_32x32x16_bf16 v[80:95], v[248:251], v[124:127], v[80:95]
	ds_read_b64_tr_b16 v[136:137], v193 offset:29696
	ds_read_b64_tr_b16 v[138:139], v193 offset:30208
	v_mfma_f32_32x32x16_bf16 v[96:111], v[128:131], v[112:115], v[64:79]
	ds_read_b64_tr_b16 v[148:149], v193 offset:32768
	ds_read_b64_tr_b16 v[150:151], v193 offset:33280
	v_mfma_f32_32x32x16_bf16 v[96:111], v[132:135], v[116:119], v[96:111]
	ds_read_b64_tr_b16 v[132:133], v193 offset:33792
	ds_read_b64_tr_b16 v[134:135], v193 offset:34304
	v_mfma_f32_32x32x16_bf16 v[96:111], v[144:147], v[120:123], v[96:111]
	ds_read_b64_tr_b16 v[144:145], v193 offset:36864
	ds_read_b64_tr_b16 v[146:147], v193 offset:37376
	v_mfma_f32_32x32x16_bf16 v[96:111], v[194:197], v[124:127], v[96:111]
	ds_read_b64_tr_b16 v[128:129], v193 offset:37888
	ds_read_b64_tr_b16 v[130:131], v193 offset:38400
	s_add_i32 s14, s28, s31
	s_cmp_lt_i32 s14, -4
	s_cbranch_scc1 .LBB0_368
	v_subrev_u32_e32 v163, 27, v192
	v_subrev_u32_e32 v162, 59, v192
	v_cmp_le_i32_e32 vcc, v163, v188
	s_nop 5
	v_cndmask_b32_e32 v96, v229, v96, vcc
	v_cmp_lt_i32_e32 vcc, v162, v188
	s_nop 1
	v_cndmask_b32_e32 v81, v229, v81, vcc
	v_cmp_le_i32_e32 vcc, v162, v188
	v_subrev_u32_e32 v162, 26, v192
	s_nop 0
	v_cndmask_b32_e32 v80, v229, v80, vcc
	v_cmp_le_i32_e32 vcc, v162, v188
	v_subrev_u32_e32 v162, 57, v192
	s_nop 0
	v_cndmask_b32_e32 v97, v229, v97, vcc
	v_cmp_le_i32_e32 vcc, v162, v188
	v_subrev_u32_e32 v162, 25, v192
	s_nop 0
	v_cndmask_b32_e32 v82, v229, v82, vcc
	v_cmp_le_i32_e32 vcc, v162, v188
	v_subrev_u32_e32 v162, 56, v192
	s_nop 0
	v_cndmask_b32_e32 v98, v229, v98, vcc
	v_cmp_le_i32_e32 vcc, v162, v188
	v_subrev_u32_e32 v162, 24, v192
	s_nop 0
	v_cndmask_b32_e32 v83, v229, v83, vcc
	v_cmp_le_i32_e32 vcc, v162, v188
	v_subrev_u32_e32 v162, 51, v192
	s_nop 0
	v_cndmask_b32_e32 v99, v229, v99, vcc
	v_cmp_le_i32_e32 vcc, v162, v188
	v_subrev_u32_e32 v162, 19, v192
	s_nop 0
	v_cndmask_b32_e32 v84, v229, v84, vcc
	v_cmp_le_i32_e32 vcc, v162, v188
	v_subrev_u32_e32 v162, 50, v192
	s_nop 0
	v_cndmask_b32_e32 v100, v229, v100, vcc
	v_cmp_le_i32_e32 vcc, v162, v188
	v_subrev_u32_e32 v162, 18, v192
	s_nop 0
	v_cndmask_b32_e32 v85, v229, v85, vcc
	v_cmp_le_i32_e32 vcc, v162, v188
	v_subrev_u32_e32 v162, 49, v192
	s_nop 0
	v_cndmask_b32_e32 v101, v229, v101, vcc
	v_cmp_le_i32_e32 vcc, v162, v188
	v_subrev_u32_e32 v162, 17, v192
	s_nop 0
	v_cndmask_b32_e32 v86, v229, v86, vcc
	v_cmp_le_i32_e32 vcc, v162, v188
	v_subrev_u32_e32 v162, 48, v192
	s_nop 0
	v_cndmask_b32_e32 v102, v229, v102, vcc
	v_cmp_le_i32_e32 vcc, v162, v188
	v_add_u32_e32 v162, -16, v192
	s_nop 0
	v_cndmask_b32_e32 v87, v229, v87, vcc
	v_cmp_le_i32_e32 vcc, v162, v188
	v_subrev_u32_e32 v162, 43, v192
	s_nop 0
	v_cndmask_b32_e32 v103, v229, v103, vcc
	v_cmp_le_i32_e32 vcc, v162, v188
	v_add_u32_e32 v162, -11, v192
	s_nop 0
	v_cndmask_b32_e32 v88, v229, v88, vcc
	v_cmp_le_i32_e32 vcc, v162, v188
	v_subrev_u32_e32 v162, 42, v192
	s_nop 0
	v_cndmask_b32_e32 v104, v229, v104, vcc
	v_cmp_le_i32_e32 vcc, v162, v188
	v_add_u32_e32 v162, -10, v192
	s_nop 0
	v_cndmask_b32_e32 v89, v229, v89, vcc
	v_cmp_le_i32_e32 vcc, v162, v188
	v_subrev_u32_e32 v162, 41, v192
	s_nop 0
	v_cndmask_b32_e32 v105, v229, v105, vcc
	v_cmp_le_i32_e32 vcc, v162, v188
	v_add_u32_e32 v162, -9, v192
	s_nop 0
	v_cndmask_b32_e32 v90, v229, v90, vcc
	v_cmp_le_i32_e32 vcc, v162, v188
	v_subrev_u32_e32 v162, 40, v192
	s_nop 0
	v_cndmask_b32_e32 v106, v229, v106, vcc
	v_cmp_le_i32_e32 vcc, v162, v188
	v_add_u32_e32 v162, -8, v192
	s_nop 0
	v_cndmask_b32_e32 v91, v229, v91, vcc
	v_cmp_le_i32_e32 vcc, v162, v188
	v_subrev_u32_e32 v162, 35, v192
	s_nop 0
	v_cndmask_b32_e32 v107, v229, v107, vcc
	v_cmp_le_i32_e32 vcc, v162, v188
	v_add_u32_e32 v162, -3, v192
	s_nop 0
	v_cndmask_b32_e32 v92, v229, v92, vcc
	v_cmp_le_i32_e32 vcc, v162, v188
	v_subrev_u32_e32 v162, 34, v192
	s_nop 0
	v_cndmask_b32_e32 v108, v229, v108, vcc
	v_cmp_le_i32_e32 vcc, v162, v188
	v_add_u32_e32 v162, -2, v192
	s_nop 0
	v_cndmask_b32_e32 v93, v229, v93, vcc
	v_cmp_le_i32_e32 vcc, v162, v188
	v_subrev_u32_e32 v162, 33, v192
	s_nop 0
	v_cndmask_b32_e32 v109, v229, v109, vcc
	v_cmp_le_i32_e32 vcc, v162, v188
	v_add_u32_e32 v162, -1, v192
	s_nop 0
	v_cndmask_b32_e32 v94, v229, v94, vcc
	v_cmp_le_i32_e32 vcc, v162, v188
	v_subrev_u32_e32 v162, 32, v192
	s_nop 0
	v_cndmask_b32_e32 v110, v229, v110, vcc
	v_cmp_le_i32_e32 vcc, v162, v188
	s_nop 1
	v_cndmask_b32_e32 v95, v229, v95, vcc
	v_cmp_le_i32_e32 vcc, v192, v188
	s_nop 1
	v_cndmask_b32_e32 v111, v229, v111, vcc
; __device__ __forceinline__ int crow(int r,int hi){return (r&3)+8*(r>>2)+4*hi;}
;   #define MX3(a,b,c) __builtin_fmaxf(__builtin_fmaxf((a),(b)),(c))
; template<int THRL> __device__ __forceinline__ void attn_unit(int qb,const bf16*Q,const bf16*__restrict__ K,const bf16*__restrict__ V,bf16*O,char*shm){
;     ...
;     float a=MX3(C0[0],C0[1],C1[0]),b=MX3(C0[2],C0[3],C1[1]); a=MX3(a,C1[2],C1[3]);
;     #pragma unroll
;     for(int r=4;r<16;r+=4){a=MX3(a,C0[r],C0[r+1]);b=MX3(b,C0[r+2],C0[r+3]);a=MX3(a,C1[r],C1[r+1]);b=MX3(b,C1[r+2],C1[r+3]);}
;     float rm=__builtin_fmaxf(a,b); { auto rr=__builtin_amdgcn_permlane32_swap(__float_as_uint(rm),__float_as_uint(rm),false,false); rm=__builtin_fmaxf(__uint_as_float(rr[0]),__uint_as_float(rr[1])); }
;     if(t==0 || __any(rm>(float)THRL)){
;       const float dl=(t==0)?rm:__builtin_fmaxf(rm,0.f); mhat+=dl;
;       #pragma unroll
;       for(int r=0;r<16;++r){C0[r]-=dl;C1[r]-=dl;}
;       #pragma unroll
;       for(int r=0;r<16;++r)negm[r]=-mhat;
;       if(t!=0){ const float f=__builtin_amdgcn_exp2f(-dl); l_reg*=f; if(hi==0)wsf[r32]=f; asm volatile("s_waitcnt lgkmcnt(0)":::"memory");
;         #pragma unroll
;         for(int d_=0;d_<4;++d_)
;           #pragma unroll
;           for(int r=0;r<16;++r)o[d_][r]*=wsf[crow(r,hi)]; } }
.LBB0_368:
	v_max3_f32 v162, v80, v81, v82
	v_max3_f32 v163, v83, v84, v85
	v_max3_f32 v162, v162, v86, v87
	v_max3_f32 v163, v163, v88, v89
	v_max3_f32 v162, v162, v90, v91
	v_max3_f32 v163, v163, v92, v93
	v_max3_f32 v162, v162, v94, v95
	v_max3_f32 v163, v163, v96, v97
	v_max3_f32 v162, v162, v98, v99
	v_max3_f32 v163, v163, v100, v101
	v_max3_f32 v162, v162, v102, v103
	v_max3_f32 v163, v163, v104, v105
	v_max3_f32 v162, v162, v106, v107
	v_max3_f32 v163, v163, v108, v109
	v_max3_f32 v162, v162, v110, v111
	v_max_f32_e32 v162, v162, v163
	v_mov_b32_e32 v163, v162
	s_nop 1
	v_permlane32_swap_b32_e32 v162, v163
	v_max_f32_e32 v184, v162, v163
	s_mov_b32 s14, 0x41000000
	v_cmp_lt_f32_e32 vcc, s14, v184
	s_cbranch_vccz .LBB0_372
	v_max_f32_e32 v64, v184, v184
	v_max_f32_e32 v64, 0, v64
	v_exp_f32_e64 v65, -v64
	s_and_saveexec_b64 s[14:15], s[4:5]
	ds_write_b32 v191, v65
	s_or_b64 exec, exec, s[14:15]
	s_waitcnt lgkmcnt(0)
	v_pk_add_f32 v[80:81], v[80:81], v[64:65] op_sel_hi:[1,0] neg_lo:[0,1] neg_hi:[0,1]
	v_pk_add_f32 v[96:97], v[96:97], v[64:65] op_sel_hi:[1,0] neg_lo:[0,1] neg_hi:[0,1]
	v_pk_add_f32 v[82:83], v[82:83], v[64:65] op_sel_hi:[1,0] neg_lo:[0,1] neg_hi:[0,1]
	v_pk_add_f32 v[98:99], v[98:99], v[64:65] op_sel_hi:[1,0] neg_lo:[0,1] neg_hi:[0,1]
	v_pk_add_f32 v[84:85], v[84:85], v[64:65] op_sel_hi:[1,0] neg_lo:[0,1] neg_hi:[0,1]
	v_pk_add_f32 v[100:101], v[100:101], v[64:65] op_sel_hi:[1,0] neg_lo:[0,1] neg_hi:[0,1]
	v_pk_add_f32 v[86:87], v[86:87], v[64:65] op_sel_hi:[1,0] neg_lo:[0,1] neg_hi:[0,1]
	v_pk_add_f32 v[102:103], v[102:103], v[64:65] op_sel_hi:[1,0] neg_lo:[0,1] neg_hi:[0,1]
	v_pk_add_f32 v[88:89], v[88:89], v[64:65] op_sel_hi:[1,0] neg_lo:[0,1] neg_hi:[0,1]
	v_pk_add_f32 v[104:105], v[104:105], v[64:65] op_sel_hi:[1,0] neg_lo:[0,1] neg_hi:[0,1]
	v_pk_add_f32 v[90:91], v[90:91], v[64:65] op_sel_hi:[1,0] neg_lo:[0,1] neg_hi:[0,1]
	v_pk_add_f32 v[106:107], v[106:107], v[64:65] op_sel_hi:[1,0] neg_lo:[0,1] neg_hi:[0,1]
	v_pk_add_f32 v[92:93], v[92:93], v[64:65] op_sel_hi:[1,0] neg_lo:[0,1] neg_hi:[0,1]
	v_pk_add_f32 v[108:109], v[108:109], v[64:65] op_sel_hi:[1,0] neg_lo:[0,1] neg_hi:[0,1]
	v_pk_add_f32 v[94:95], v[94:95], v[64:65] op_sel_hi:[1,0] neg_lo:[0,1] neg_hi:[0,1]
	v_pk_add_f32 v[110:111], v[110:111], v[64:65] op_sel_hi:[1,0] neg_lo:[0,1] neg_hi:[0,1]
	v_pk_add_f32 v[184:185], v[178:179], v[64:65]
	v_pk_mul_f32 v[76:77], v[178:179], v[64:65]
	ds_read_b128 v[64:67], v160 offset:64
	ds_read_b128 v[68:71], v160 offset:96
	ds_read_b128 v[72:75], v160
	ds_read_b128 v[194:197], v160 offset:32
	v_mov_b32_e32 v185, v77
	v_pk_add_f32 v[78:79], v[184:185], 0 neg_lo:[1,1] neg_hi:[1,1]
	s_waitcnt lgkmcnt(2)
	v_pk_mul_f32 v[60:61], v[60:61], v[68:69]
	v_pk_mul_f32 v[56:57], v[56:57], v[64:65]
	s_waitcnt lgkmcnt(0)
	v_pk_mul_f32 v[52:53], v[52:53], v[194:195]
	v_pk_mul_f32 v[62:63], v[62:63], v[70:71]
	v_pk_mul_f32 v[58:59], v[58:59], v[66:67]
	v_pk_mul_f32 v[54:55], v[54:55], v[196:197]
	v_pk_mul_f32 v[50:51], v[50:51], v[74:75]
	v_pk_mul_f32 v[48:49], v[48:49], v[72:73]
	v_pk_mul_f32 v[44:45], v[44:45], v[68:69]
	v_pk_mul_f32 v[40:41], v[40:41], v[64:65]
	v_pk_mul_f32 v[36:37], v[36:37], v[194:195]
	v_pk_mul_f32 v[46:47], v[46:47], v[70:71]
	v_pk_mul_f32 v[42:43], v[42:43], v[66:67]
	v_pk_mul_f32 v[38:39], v[38:39], v[196:197]
	v_pk_mul_f32 v[34:35], v[34:35], v[74:75]
	v_pk_mul_f32 v[32:33], v[32:33], v[72:73]
	v_pk_mul_f32 v[28:29], v[28:29], v[68:69]
	v_pk_mul_f32 v[24:25], v[24:25], v[64:65]
	v_pk_mul_f32 v[20:21], v[20:21], v[194:195]
	v_pk_mul_f32 v[30:31], v[30:31], v[70:71]
	v_pk_mul_f32 v[26:27], v[26:27], v[66:67]
	v_pk_mul_f32 v[22:23], v[22:23], v[196:197]
	v_pk_mul_f32 v[18:19], v[18:19], v[74:75]
	v_pk_mul_f32 v[16:17], v[16:17], v[72:73]
	v_pk_mul_f32 v[12:13], v[12:13], v[68:69]
	v_pk_mul_f32 v[8:9], v[8:9], v[64:65]
	v_pk_mul_f32 v[4:5], v[4:5], v[194:195]
	v_pk_mul_f32 v[14:15], v[14:15], v[70:71]
	v_pk_mul_f32 v[10:11], v[10:11], v[66:67]
	v_pk_mul_f32 v[6:7], v[6:7], v[196:197]
	v_pk_mul_f32 v[2:3], v[2:3], v[74:75]
	v_pk_mul_f32 v[0:1], v[0:1], v[72:73]
	v_mov_b32_e32 v79, v78
	v_mov_b32_e32 v77, v78
	v_mov_b32_e32 v76, v78
	v_mov_b32_e32 v75, v78
	v_mov_b32_e32 v74, v78
	v_mov_b32_e32 v73, v78
	v_mov_b32_e32 v72, v78
	v_mov_b32_e32 v71, v78
	v_mov_b32_e32 v70, v78
	v_mov_b32_e32 v69, v78
	v_mov_b32_e32 v68, v78
	v_mov_b32_e32 v67, v78
	v_mov_b32_e32 v66, v78
	v_mov_b32_e32 v65, v78
	v_mov_b32_e32 v64, v78
	v_mov_b64_e32 v[178:179], v[184:185]

; #define SBAR() __builtin_amdgcn_sched_barrier(0)
; #define WAIT_BAR(N) asm volatile("s_waitcnt vmcnt(" #N ") lgkmcnt(0)\n\ts_barrier":::"memory")
;   #define ROT3() do{ const int x_=c0; c0=c1; c1=c2; c2=x_; }while(0)
; template<int THRL> __device__ __forceinline__ void attn_unit(int qb,const bf16*Q,const bf16*__restrict__ K,const bf16*__restrict__ V,bf16*O,char*shm){
;     ...
;     for(int d_=0;d_<4;++d_){ o[d_]=__builtin_amdgcn_mfma_f32_32x32x16_bf16(__builtin_bit_cast(bf16x8,pw1),VFRAG(vl_,vh_,d_*2+1),o[d_],0,0,0); }
;     #pragma unroll
;     for(int d_=0;d_<4;++d_){ o[d_]=__builtin_amdgcn_mfma_f32_32x32x16_bf16(__builtin_bit_cast(bf16x8,pw2),VFRAG(w2l_,w2h_,d_),o[d_],0,0,0); }
;     #pragma unroll
;     for(int d_=0;d_<4;++d_){ o[d_]=__builtin_amdgcn_mfma_f32_32x32x16_bf16(__builtin_bit_cast(bf16x8,pw3),VFRAG(w3l_,w3h_,d_),o[d_],0,0,0); }
;     SBAR();
;     ...
;     if(t+2<NT){WAIT_BAR(3);}else{WAIT_BAR(0);}
;     ROT3();
.Lattn_nodma2:
	ds_read_b128 v[244:247], v164 offset:4096
	v_exp_f32_e32 v108, v108
	v_exp_f32_e32 v109, v109
	v_cvt_pk_bf16_f32 v207, v106, v107
	v_add_f32_e32 v80, v86, v80
	s_waitcnt lgkmcnt(13)
	v_mfma_f32_32x32x16_bf16 v[16:31], v[202:205], v[218:221], v[16:31]
	ds_read_b128 v[248:251], v164 offset:6144
	v_exp_f32_e32 v110, v110
	v_exp_f32_e32 v111, v111
	v_cvt_pk_bf16_f32 v208, v108, v109
	v_add_f32_e32 v80, v87, v80
	s_waitcnt lgkmcnt(12)
	v_mfma_f32_32x32x16_bf16 v[0:15], v[202:205], v[232:235], v[0:15]
	ds_read_b128 v[194:197], v164 offset:6656
	v_cvt_pk_bf16_f32 v209, v110, v111
	v_add_f32_e32 v81, v96, v97
	v_add_f32_e32 v80, v88, v80
	v_add_f32_e32 v81, v98, v81
	v_add_u32_e32 v192, 64, v192
	v_lshl_add_u64 v[180:181], v[180:181], 0, s[88:89]
	v_lshl_add_u64 v[182:183], v[182:183], 0, s[88:89]
	s_waitcnt lgkmcnt(5)
	v_mfma_f32_32x32x16_bf16 v[48:63], v[206:209], v[144:147], v[48:63]
	ds_read_b128 v[144:147], v164 offset:4608
	v_add_f32_e32 v80, v89, v80
	v_add_f32_e32 v81, v99, v81
	v_add_f32_e32 v80, v90, v80
	v_add_f32_e32 v81, v100, v81
	v_add_f32_e32 v80, v91, v80
	v_add_f32_e32 v81, v101, v81
	s_add_i32 s31, s31, 1
	s_lshl_b32 s14, s27, 14
	v_add_u32_e32 v193, s14, v190
	v_mfma_f32_32x32x16_bf16 v[32:47], v[206:209], v[148:151], v[32:47]
	ds_read_b128 v[132:135], v164 offset:2560
	v_add_f32_e32 v80, v92, v80
	v_add_f32_e32 v81, v102, v81
	v_add_f32_e32 v80, v93, v80
	v_add_f32_e32 v81, v103, v81
	v_add_f32_e32 v80, v94, v80
	v_add_f32_e32 v81, v104, v81
	s_mov_b32 s35, s27
	s_mov_b32 s27, s29
	s_mov_b32 s29, s34
	s_mov_b32 s34, s35
	v_mfma_f32_32x32x16_bf16 v[16:31], v[206:209], v[152:155], v[16:31]
	ds_read_b128 v[128:131], v164 offset:512
	v_add_f32_e32 v80, v95, v80
	v_add_f32_e32 v81, v105, v81
	v_add_f32_e32 v81, v106, v81
	v_add_f32_e32 v81, v107, v81
	v_add_f32_e32 v81, v108, v81
	v_add_f32_e32 v81, v109, v81
	s_add_i32 s12, s31, 3
	s_cmp_ge_i32 s12, s26
	s_cselect_b64 s[12:13], -1, 0
	v_mfma_f32_32x32x16_bf16 v[0:15], v[206:209], v[156:159], v[0:15]
	v_add_f32_e32 v81, v110, v81
	v_add_f32_e32 v81, v111, v81
	v_add_f32_e32 v80, v81, v80
	v_add_f32_e32 v179, v179, v80
	s_add_i32 s14, s28, s31
	s_cbranch_vccnz .Lattn_tailbar
	s_cmp_eq_u32 s14, 0
	s_waitcnt vmcnt(3) lgkmcnt(0)
	s_barrier
	s_cbranch_scc0 .Lattn_top
	s_branch .LBB0_379
.Lattn_tailbar:
	s_cmp_eq_u32 s14, 0
	s_waitcnt vmcnt(0) lgkmcnt(0)
	s_barrier
	s_cbranch_scc0 .Lattn_top
	s_branch .LBB0_379
